# queue items: gla_load batched loads; prep w_up/a_up hoisted to registers with unrolled j-loop
# speedup vs baseline: 1.0883x; 1.0242x over previous
; __device__ __forceinline__ float bf2f(u16 h) { return __uint_as_float(((u32)h) << 16); }
; __device__ void gla_load(const Params& p, int l, int b, int h, int c, float* qs, float* ks, float* vs, float* bc, float* gds) {
;     ...
;   for (int e = tid; e < 64 * 32; e += NT) {
;     const int t = e >> 5, k = e & 31;
;     const u16* pr = proj + (tok0 + t) * INW + GL0;
;     qs[e] = bf2f(pr[h * 32 + k]) * qsc;
;     ks[e] = bf2f(pr[128 + h * 32 + k]);
;   }
;   for (int e = tid; e < 64 * 64; e += NT) {
;     const int t = e >> 6, v = e & 63;
;     vs[e] = bf2f(proj[(tok0 + t) * INW + GL0 + 256 + h * 64 + v]);
;   }
;   for (int e = tid; e < 64 * 16; e += NT) {
;     const int t = e >> 4, j = e & 15;
;     gds[e] = bf2f(proj[(tok0 + t) * INW + GL0 + 512 + j]);
;   }
.LBB0_417:
	s_or_b64 exec, exec, s[0:1]
	s_add_i32 s18, s79, 0xfffff500
	s_and_b32 s17, s79, 63
	s_lshl_b32 s0, s18, 4
	s_and_b32 s0, s0, 0x3000
	s_lshl_b32 s1, s17, 6
	v_mov_b32_e32 v2, v68
	s_or_b32 s8, s0, s1
	s_movk_i32 s0, 0x7ff
	s_barrier
	s_bfe_u32 s16, s79, 0x20006
	v_cmp_lt_i32_e64 s[6:7], s0, v2
	s_movk_i32 s0, 0x800
	s_mov_b32 s9, s99
	v_lshrrev_b32_e32 v3, 5, v2
	v_add_u32_e32 v3, s8, v3
	v_mov_b64_e32 v[10:11], s[76:77]
	v_mad_i64_i32 v[10:11], s[0:1], v3, s83, v[10:11]
	v_and_b32_e32 v7, 31, v2
	v_lshl_or_b32 v7, s16, 5, v7
	v_lshlrev_b32_e32 v8, 1, v7
	v_mov_b32_e32 v9, 0
	v_lshl_add_u64 v[10:11], v[10:11], 0, v[8:9]
	v_add_co_u32_e32 v10, vcc, 0x1300, v10
	s_nop 1
	v_addc_co_u32_e32 v11, vcc, 0, v11, vcc
	v_add_co_u32_e32 v12, vcc, 0x19200, v10
	s_nop 1
	v_addc_co_u32_e32 v13, vcc, 0, v11, vcc
	v_add_co_u32_e32 v14, vcc, 0x19200, v12
	s_nop 1
	v_addc_co_u32_e32 v15, vcc, 0, v13, vcc
	v_add_co_u32_e32 v16, vcc, 0x19200, v14
	s_nop 1
	v_addc_co_u32_e32 v17, vcc, 0, v15, vcc
	global_load_ushort v40, v[10:11], off
	global_load_ushort v44, v[10:11], off offset:256
	global_load_ushort v41, v[12:13], off
	global_load_ushort v45, v[12:13], off offset:256
	global_load_ushort v42, v[14:15], off
	global_load_ushort v46, v[14:15], off offset:256
	global_load_ushort v43, v[16:17], off
	global_load_ushort v47, v[16:17], off offset:256
	v_lshrrev_b32_e32 v3, 6, v2
	v_add_u32_e32 v3, s8, v3
	v_mov_b64_e32 v[18:19], s[76:77]
	v_mad_i64_i32 v[18:19], s[0:1], v3, s83, v[18:19]
	v_and_b32_e32 v7, 63, v2
	v_lshl_or_b32 v7, s16, 6, v7
	v_lshlrev_b32_e32 v8, 1, v7
	v_mov_b32_e32 v9, 0
	v_lshl_add_u64 v[18:19], v[18:19], 0, v[8:9]
	v_add_co_u32_e32 v18, vcc, 0x1500, v18
	s_nop 1
	v_addc_co_u32_e32 v19, vcc, 0, v19, vcc
	v_add_co_u32_e32 v20, vcc, 0xc900, v18
	s_nop 1
	v_addc_co_u32_e32 v21, vcc, 0, v19, vcc
	v_add_co_u32_e32 v22, vcc, 0xc900, v20
	s_nop 1
	v_addc_co_u32_e32 v23, vcc, 0, v21, vcc
	v_add_co_u32_e32 v24, vcc, 0xc900, v22
	s_nop 1
	v_addc_co_u32_e32 v25, vcc, 0, v23, vcc
	v_add_co_u32_e32 v26, vcc, 0xc900, v24
	s_nop 1
	v_addc_co_u32_e32 v27, vcc, 0, v25, vcc
	v_add_co_u32_e32 v28, vcc, 0xc900, v26
	s_nop 1
	v_addc_co_u32_e32 v29, vcc, 0, v27, vcc
	v_add_co_u32_e32 v30, vcc, 0xc900, v28
	s_nop 1
	v_addc_co_u32_e32 v31, vcc, 0, v29, vcc
	v_add_co_u32_e32 v32, vcc, 0xc900, v30
	s_nop 1
	v_addc_co_u32_e32 v33, vcc, 0, v31, vcc
	global_load_ushort v48, v[18:19], off
	global_load_ushort v49, v[20:21], off
	global_load_ushort v50, v[22:23], off
	global_load_ushort v51, v[24:25], off
	global_load_ushort v52, v[26:27], off
	global_load_ushort v53, v[28:29], off
	global_load_ushort v54, v[30:31], off
	global_load_ushort v55, v[32:33], off
	v_lshrrev_b32_e32 v3, 4, v2
	v_add_u32_e32 v3, s8, v3
	v_mov_b64_e32 v[34:35], s[76:77]
	v_mad_i64_i32 v[34:35], s[0:1], v3, s83, v[34:35]
	v_and_b32_e32 v7, 15, v2
	v_lshlrev_b32_e32 v8, 1, v7
	v_mov_b32_e32 v9, 0
	v_lshl_add_u64 v[34:35], v[34:35], 0, v[8:9]
	v_add_co_u32_e32 v34, vcc, 0x1700, v34
	s_nop 1
	v_addc_co_u32_e32 v35, vcc, 0, v35, vcc
	v_add_co_u32_e32 v36, vcc, 0x32400, v34
	s_nop 1
	v_addc_co_u32_e32 v37, vcc, 0, v35, vcc
	global_load_ushort v56, v[34:35], off
	global_load_ushort v57, v[36:37], off
	v_lshl_add_u32 v10, v2, 2, v94
	v_add_u32_e32 v11, 0x4000, v10
	v_add_u32_e32 v12, 0x10000, v10
	s_waitcnt vmcnt(10)
	v_lshlrev_b32_e32 v40, 16, v40
	v_lshlrev_b32_e32 v41, 16, v41
	v_lshlrev_b32_e32 v42, 16, v42
	v_lshlrev_b32_e32 v43, 16, v43
	v_lshlrev_b32_e32 v44, 16, v44
	v_lshlrev_b32_e32 v45, 16, v45
	v_lshlrev_b32_e32 v46, 16, v46
	v_lshlrev_b32_e32 v47, 16, v47
	v_mul_f32_e32 v40, 0x3e3504f3, v40
	v_mul_f32_e32 v41, 0x3e3504f3, v41
	v_mul_f32_e32 v42, 0x3e3504f3, v42
	v_mul_f32_e32 v43, 0x3e3504f3, v43
	ds_write2st64_b32 v10, v40, v41 offset1:8
	ds_write2st64_b32 v10, v42, v43 offset0:16 offset1:24
	ds_write2st64_b32 v10, v44, v45 offset0:32 offset1:40
	ds_write2st64_b32 v10, v46, v47 offset0:48 offset1:56
	s_waitcnt vmcnt(2)
	v_lshlrev_b32_e32 v48, 16, v48
	v_lshlrev_b32_e32 v49, 16, v49
	v_lshlrev_b32_e32 v50, 16, v50
	v_lshlrev_b32_e32 v51, 16, v51
	v_lshlrev_b32_e32 v52, 16, v52
	v_lshlrev_b32_e32 v53, 16, v53
	v_lshlrev_b32_e32 v54, 16, v54
	v_lshlrev_b32_e32 v55, 16, v55
	ds_write2st64_b32 v11, v48, v49 offset0:0 offset1:8
	ds_write2st64_b32 v11, v50, v51 offset0:16 offset1:24
	ds_write2st64_b32 v11, v52, v53 offset0:32 offset1:40
	ds_write2st64_b32 v11, v54, v55 offset0:48 offset1:56
	s_waitcnt vmcnt(0)
	v_lshlrev_b32_e32 v56, 16, v56
	v_lshlrev_b32_e32 v57, 16, v57
	ds_write2st64_b32 v12, v56, v57 offset1:8

; __device__ __forceinline__ float bf2f(u16 h) { return __uint_as_float(((u32)h) << 16); }
; __device__ void gla_load(const Params& p, int l, int b, int h, int c, float* qs, float* ks, float* vs, float* bc, float* gds) {
;     ...
;   for (int e = tid; e < 64 * 32; e += NT) {
;     const int t = e >> 5, k = e & 31;
;     const u16* pr = proj + (tok0 + t) * INW + GL0;
;     qs[e] = bf2f(pr[h * 32 + k]) * qsc;
;     ks[e] = bf2f(pr[128 + h * 32 + k]);
;   }
;   for (int e = tid; e < 64 * 64; e += NT) {
;     const int t = e >> 6, v = e & 63;
;     vs[e] = bf2f(proj[(tok0 + t) * INW + GL0 + 256 + h * 64 + v]);
;   }
;   for (int e = tid; e < 64 * 16; e += NT) {
;     const int t = e >> 4, j = e & 15;
;     gds[e] = bf2f(proj[(tok0 + t) * INW + GL0 + 512 + j]);
;   }
.LBB0_518:
	s_andn2_b64 vcc, exec, s[0:1]
	s_cbranch_vccnz .LBB0_573
	s_add_i32 s8, s79, 0xfffffc00
	s_lshl_b32 s0, s8, 4
	s_lshl_b32 s1, s8, 6
	s_and_b32 s0, s0, 0x3000
	s_and_b32 s1, s1, 0xfc0
	v_mov_b32_e32 v2, v68
	s_or_b32 s16, s1, s0
	s_movk_i32 s0, 0x7ff
	s_bfe_u32 s9, s79, 0x20006
	v_cmp_lt_i32_e64 s[6:7], s0, v2
	s_movk_i32 s0, 0x800
	v_lshrrev_b32_e32 v3, 5, v2
	v_add_u32_e32 v3, s16, v3
	v_mov_b64_e32 v[10:11], s[76:77]
	v_mad_i64_i32 v[10:11], s[0:1], v3, s83, v[10:11]
	v_and_b32_e32 v7, 31, v2
	v_lshl_or_b32 v7, s9, 5, v7
	v_lshlrev_b32_e32 v8, 1, v7
	v_mov_b32_e32 v9, 0
	v_lshl_add_u64 v[10:11], v[10:11], 0, v[8:9]
	v_add_co_u32_e32 v10, vcc, 0x1300, v10
	s_nop 1
	v_addc_co_u32_e32 v11, vcc, 0, v11, vcc
	v_add_co_u32_e32 v12, vcc, 0x19200, v10
	s_nop 1
	v_addc_co_u32_e32 v13, vcc, 0, v11, vcc
	v_add_co_u32_e32 v14, vcc, 0x19200, v12
	s_nop 1
	v_addc_co_u32_e32 v15, vcc, 0, v13, vcc
	v_add_co_u32_e32 v16, vcc, 0x19200, v14
	s_nop 1
	v_addc_co_u32_e32 v17, vcc, 0, v15, vcc
	global_load_ushort v40, v[10:11], off
	global_load_ushort v44, v[10:11], off offset:256
	global_load_ushort v41, v[12:13], off
	global_load_ushort v45, v[12:13], off offset:256
	global_load_ushort v42, v[14:15], off
	global_load_ushort v46, v[14:15], off offset:256
	global_load_ushort v43, v[16:17], off
	global_load_ushort v47, v[16:17], off offset:256
	v_lshrrev_b32_e32 v3, 6, v2
	v_add_u32_e32 v3, s16, v3
	v_mov_b64_e32 v[18:19], s[76:77]
	v_mad_i64_i32 v[18:19], s[0:1], v3, s83, v[18:19]
	v_and_b32_e32 v7, 63, v2
	v_lshl_or_b32 v7, s9, 6, v7
	v_lshlrev_b32_e32 v8, 1, v7
	v_mov_b32_e32 v9, 0
	v_lshl_add_u64 v[18:19], v[18:19], 0, v[8:9]
	v_add_co_u32_e32 v18, vcc, 0x1500, v18
	s_nop 1
	v_addc_co_u32_e32 v19, vcc, 0, v19, vcc
	v_add_co_u32_e32 v20, vcc, 0xc900, v18
	s_nop 1
	v_addc_co_u32_e32 v21, vcc, 0, v19, vcc
	v_add_co_u32_e32 v22, vcc, 0xc900, v20
	s_nop 1
	v_addc_co_u32_e32 v23, vcc, 0, v21, vcc
	v_add_co_u32_e32 v24, vcc, 0xc900, v22
	s_nop 1
	v_addc_co_u32_e32 v25, vcc, 0, v23, vcc
	v_add_co_u32_e32 v26, vcc, 0xc900, v24
	s_nop 1
	v_addc_co_u32_e32 v27, vcc, 0, v25, vcc
	v_add_co_u32_e32 v28, vcc, 0xc900, v26
	s_nop 1
	v_addc_co_u32_e32 v29, vcc, 0, v27, vcc
	v_add_co_u32_e32 v30, vcc, 0xc900, v28
	s_nop 1
	v_addc_co_u32_e32 v31, vcc, 0, v29, vcc
	v_add_co_u32_e32 v32, vcc, 0xc900, v30
	s_nop 1
	v_addc_co_u32_e32 v33, vcc, 0, v31, vcc
	global_load_ushort v48, v[18:19], off
	global_load_ushort v49, v[20:21], off
	global_load_ushort v50, v[22:23], off
	global_load_ushort v51, v[24:25], off
	global_load_ushort v52, v[26:27], off
	global_load_ushort v53, v[28:29], off
	global_load_ushort v54, v[30:31], off
	global_load_ushort v55, v[32:33], off
	v_lshrrev_b32_e32 v3, 4, v2
	v_add_u32_e32 v3, s16, v3
	v_mov_b64_e32 v[34:35], s[76:77]
	v_mad_i64_i32 v[34:35], s[0:1], v3, s83, v[34:35]
	v_and_b32_e32 v7, 15, v2
	v_lshlrev_b32_e32 v8, 1, v7
	v_mov_b32_e32 v9, 0
	v_lshl_add_u64 v[34:35], v[34:35], 0, v[8:9]
	v_add_co_u32_e32 v34, vcc, 0x1700, v34
	s_nop 1
	v_addc_co_u32_e32 v35, vcc, 0, v35, vcc
	v_add_co_u32_e32 v36, vcc, 0x32400, v34
	s_nop 1
	v_addc_co_u32_e32 v37, vcc, 0, v35, vcc
	global_load_ushort v56, v[34:35], off
	global_load_ushort v57, v[36:37], off
	v_lshl_add_u32 v10, v2, 2, v94
	v_add_u32_e32 v11, 0x4000, v10
	v_add_u32_e32 v12, 0x10000, v10
	s_waitcnt vmcnt(10)
	v_lshlrev_b32_e32 v40, 16, v40
	v_lshlrev_b32_e32 v41, 16, v41
	v_lshlrev_b32_e32 v42, 16, v42
	v_lshlrev_b32_e32 v43, 16, v43
	v_lshlrev_b32_e32 v44, 16, v44
	v_lshlrev_b32_e32 v45, 16, v45
	v_lshlrev_b32_e32 v46, 16, v46
	v_lshlrev_b32_e32 v47, 16, v47
	v_mul_f32_e32 v40, 0x3e3504f3, v40
	v_mul_f32_e32 v41, 0x3e3504f3, v41
	v_mul_f32_e32 v42, 0x3e3504f3, v42
	v_mul_f32_e32 v43, 0x3e3504f3, v43
	ds_write2st64_b32 v10, v40, v41 offset1:8
	ds_write2st64_b32 v10, v42, v43 offset0:16 offset1:24
	ds_write2st64_b32 v10, v44, v45 offset0:32 offset1:40
	ds_write2st64_b32 v10, v46, v47 offset0:48 offset1:56
	s_waitcnt vmcnt(2)
	v_lshlrev_b32_e32 v48, 16, v48
	v_lshlrev_b32_e32 v49, 16, v49
	v_lshlrev_b32_e32 v50, 16, v50
	v_lshlrev_b32_e32 v51, 16, v51
	v_lshlrev_b32_e32 v52, 16, v52
	v_lshlrev_b32_e32 v53, 16, v53
	v_lshlrev_b32_e32 v54, 16, v54
	v_lshlrev_b32_e32 v55, 16, v55
	ds_write2st64_b32 v11, v48, v49 offset0:0 offset1:8
	ds_write2st64_b32 v11, v50, v51 offset0:16 offset1:24
	ds_write2st64_b32 v11, v52, v53 offset0:32 offset1:40
	ds_write2st64_b32 v11, v54, v55 offset0:48 offset1:56
	s_waitcnt vmcnt(0)
	v_lshlrev_b32_e32 v56, 16, v56
	v_lshlrev_b32_e32 v57, 16, v57
	ds_write2st64_b32 v12, v56, v57 offset1:8

; __device__ __forceinline__ float bf2f(u16 h) { return __uint_as_float(((u32)h) << 16); }
; __device__ __forceinline__ int opaque_tid() { int t = threadIdx.x; asm volatile("" : "+v"(t)); return t; }
; __device__ void rwprep_items(const Params& p, int l, unsigned char* ldsraw, int it_begin, int it_end, int it_step) {
;     ...
;   const float* mu = p.in[4] + l * 1280;
;   const float* w0 = p.in[5] + l * 384;
;   const float* w_up = p.in[6] + l * 32 * 384;
;   const float* a0 = p.in[7] + l * 384;
;   const float* a_up = p.in[8] + l * 32 * 384;
;   const float* k_k = p.in[10] + l * 384;
;   const float* k_a = p.in[11] + l * 384;
;   const float* r_k = p.in[12] + l * 384;
;   float* bon = (float*)(p.ws + WS_CTRL + 65536);
;   const int tid = opaque_tid();
;   for (int it = it_begin; it < it_end; it += it_step) {
;     const int tok0 = it * 4;
;     if (tid < 256) {
;       const int tt = tid >> 6, j = tid & 63;
;       const int tok = tok0 + tt;
;       const int col = 1152 + j;
;       const float pc = bf2f(proj[(size_t)tok * INW + RW0 + col]);
;       const float pp = (tok % T == 0) ? 0.f : bf2f(proj[(size_t)(tok - 1) * INW + RW0 + col]);
;       float s = pc + (pp - pc) * mu[col];
;       if (j < 32) { const float e2 = __expf(2.f * s); s = 1.f - 2.f / (e2 + 1.f); }
;       codes[tt * 64 + j] = s;
;     }
;     __syncthreads();
;     if (tid < 384) {
;       const int c = tid;
;       float aw[4], aa[4];
;       float pr_[5], pk_[5], pv_[5];
; #pragma unroll
;       for (int tt = 0; tt < 4; ++tt) { aw[tt] = 0.f; aa[tt] = 0.f; }
; #pragma unroll
;       for (int tt = 0; tt < 5; ++tt) {
;         const int tok = tok0 + tt - 1;
;         const bool ok = (tt > 0) || (tok0 % T != 0);
;         const u16* pq = proj + (size_t)(ok ? tok : tok0) * INW + RW0;
;         pr_[tt] = ok ? bf2f(pq[c]) : 0.f; pk_[tt] = ok ? bf2f(pq[384 + c]) : 0.f; pv_[tt] = ok ? bf2f(pq[768 + c]) : 0.f;
;       }
; #pragma unroll 4
;       for (int j = 0; j < 32; ++j) {
;         const float wu = w_up[j * 384 + c], au = a_up[j * 384 + c];
.LBB0_574:
	s_andn2_b64 vcc, exec, s[0:1]
	s_cbranch_vccnz .LBB0_601
	s_bfe_u32 s15, s79, 0x20002
	s_ashr_i32 s14, s79, 4
	s_lshl_b32 s0, s15, 12
	s_lshl_b32 s1, s14, 6
	s_add_i32 s0, s0, s1
	s_lshl_b32 s1, s79, 2
	s_ashr_i32 s0, s0, 2
	s_and_b32 s1, s1, 12
	s_or_b32 s18, s0, s1
	v_mov_b32_e32 v2, v68
	s_movk_i32 s0, 0x100
	s_or_b32 s19, s18, 3
	v_cmp_gt_i32_e64 s[6:7], s0, v2
	v_ashrrev_i32_e32 v3, 31, v2
	v_readlane_b32 s0, v160, 52
	v_lshlrev_b64 v[30:31], 2, v[2:3]
	v_readlane_b32 s1, v160, 53
	v_and_b32_e32 v5, 63, v2
	v_ashrrev_i32_e32 v4, 6, v2
	v_lshl_add_u64 v[14:15], s[0:1], 0, v[30:31]
	v_readlane_b32 s0, v160, 50
	v_readlane_b32 s1, v160, 51
	v_or_b32_e32 v8, 0x480, v5
	v_lshlrev_b32_e32 v0, 2, v8
	v_lshl_add_u64 v[16:17], s[0:1], 0, v[30:31]
	v_readlane_b32 s0, v160, 48
	v_readlane_b32 s1, v160, 49
	v_cmp_gt_u32_e64 s[8:9], 32, v5
	v_cmp_eq_u32_e64 s[12:13], 0, v5
	v_lshl_add_u64 v[18:19], s[0:1], 0, v[30:31]
	v_readlane_b32 s0, v160, 46
	v_readlane_b32 s1, v160, 47
	v_ashrrev_i32_e32 v5, 31, v4
	v_lshl_add_u64 v[10:11], s[44:45], 0, v[0:1]
	v_lshl_add_u64 v[20:21], s[0:1], 0, v[30:31]
	v_readlane_b32 s0, v160, 44
	v_readlane_b32 s1, v160, 45
	v_lshl_add_u32 v7, v2, 2, v94
	v_cmp_gt_i32_e64 s[10:11], s41, v2
	v_lshl_add_u64 v[22:23], s[0:1], 0, v[30:31]
	v_readlane_b32 s0, v162, 33
	v_readlane_b32 s1, v162, 34
	v_lshl_add_u64 v[12:13], s[44:45], 0, v[30:31]
	v_lshl_add_u64 v[26:27], v[2:3], 1, s[76:77]
	v_lshl_add_u64 v[24:25], v[4:5], 2, s[0:1]
	v_lshl_add_u64 v[28:29], s[94:95], 0, v[30:31]
	v_lshl_add_u64 v[30:31], s[90:91], 0, v[30:31]
	s_and_saveexec_b64 s[0:1], s[10:11]
	v_add_co_u32_e32 v228, vcc, 0x600, v28
	s_nop 1
	v_addc_co_u32_e32 v229, vcc, 0, v29, vcc
	v_add_co_u32_e32 v230, vcc, 0x600, v30
	s_nop 1
	v_addc_co_u32_e32 v231, vcc, 0, v31, vcc
	global_load_dword v164, v[228:229], off offset:-1536
	global_load_dword v165, v[230:231], off offset:-1536
	global_load_dword v166, v[228:229], off
	global_load_dword v167, v[230:231], off
	global_load_dword v168, v[228:229], off offset:1536
	global_load_dword v169, v[230:231], off offset:1536
	global_load_dword v170, v[228:229], off offset:3072
	global_load_dword v171, v[230:231], off offset:3072
	v_lshl_add_u64 v[228:229], v[228:229], 0, s[92:93]
	v_lshl_add_u64 v[230:231], v[230:231], 0, s[92:93]
	global_load_dword v172, v[228:229], off offset:-1536
	global_load_dword v173, v[230:231], off offset:-1536
	global_load_dword v174, v[228:229], off
	global_load_dword v175, v[230:231], off
	global_load_dword v176, v[228:229], off offset:1536
	global_load_dword v177, v[230:231], off offset:1536
	global_load_dword v178, v[228:229], off offset:3072
	global_load_dword v179, v[230:231], off offset:3072
	v_lshl_add_u64 v[228:229], v[228:229], 0, s[92:93]
	v_lshl_add_u64 v[230:231], v[230:231], 0, s[92:93]
	global_load_dword v180, v[228:229], off offset:-1536
	global_load_dword v181, v[230:231], off offset:-1536
	global_load_dword v182, v[228:229], off
	global_load_dword v183, v[230:231], off
	global_load_dword v184, v[228:229], off offset:1536
	global_load_dword v185, v[230:231], off offset:1536
	global_load_dword v186, v[228:229], off offset:3072
	global_load_dword v187, v[230:231], off offset:3072
	v_lshl_add_u64 v[228:229], v[228:229], 0, s[92:93]
	v_lshl_add_u64 v[230:231], v[230:231], 0, s[92:93]
	global_load_dword v188, v[228:229], off offset:-1536
	global_load_dword v189, v[230:231], off offset:-1536
	global_load_dword v190, v[228:229], off
	global_load_dword v191, v[230:231], off
	global_load_dword v192, v[228:229], off offset:1536
	global_load_dword v193, v[230:231], off offset:1536
	global_load_dword v194, v[228:229], off offset:3072
	global_load_dword v195, v[230:231], off offset:3072
	v_lshl_add_u64 v[228:229], v[228:229], 0, s[92:93]
	v_lshl_add_u64 v[230:231], v[230:231], 0, s[92:93]
	global_load_dword v196, v[228:229], off offset:-1536
	global_load_dword v197, v[230:231], off offset:-1536
	global_load_dword v198, v[228:229], off
	global_load_dword v199, v[230:231], off
	global_load_dword v200, v[228:229], off offset:1536
	global_load_dword v201, v[230:231], off offset:1536
	global_load_dword v202, v[228:229], off offset:3072
	global_load_dword v203, v[230:231], off offset:3072
	v_lshl_add_u64 v[228:229], v[228:229], 0, s[92:93]
	v_lshl_add_u64 v[230:231], v[230:231], 0, s[92:93]
	global_load_dword v204, v[228:229], off offset:-1536
	global_load_dword v205, v[230:231], off offset:-1536
	global_load_dword v206, v[228:229], off
	global_load_dword v207, v[230:231], off
	global_load_dword v208, v[228:229], off offset:1536
	global_load_dword v209, v[230:231], off offset:1536
	global_load_dword v210, v[228:229], off offset:3072
	global_load_dword v211, v[230:231], off offset:3072
	v_lshl_add_u64 v[228:229], v[228:229], 0, s[92:93]
	v_lshl_add_u64 v[230:231], v[230:231], 0, s[92:93]
	global_load_dword v212, v[228:229], off offset:-1536
	global_load_dword v213, v[230:231], off offset:-1536
	global_load_dword v214, v[228:229], off
	global_load_dword v215, v[230:231], off
	global_load_dword v216, v[228:229], off offset:1536
	global_load_dword v217, v[230:231], off offset:1536
	global_load_dword v218, v[228:229], off offset:3072
	global_load_dword v219, v[230:231], off offset:3072
	v_lshl_add_u64 v[228:229], v[228:229], 0, s[92:93]
	v_lshl_add_u64 v[230:231], v[230:231], 0, s[92:93]
	global_load_dword v220, v[228:229], off offset:-1536
	global_load_dword v221, v[230:231], off offset:-1536
	global_load_dword v222, v[228:229], off
	global_load_dword v223, v[230:231], off
	global_load_dword v224, v[228:229], off offset:1536
	global_load_dword v225, v[230:231], off offset:1536
	global_load_dword v226, v[228:229], off offset:3072
	global_load_dword v227, v[230:231], off offset:3072
	s_or_b64 exec, exec, s[0:1]
	s_branch .LBB0_578

; __device__ __forceinline__ float bf2f(u16 h) { return __uint_as_float(((u32)h) << 16); }
; __device__ void rwprep_items(const Params& p, int l, unsigned char* ldsraw, int it_begin, int it_end, int it_step) {
;     ...
;       float pr_[5], pk_[5], pv_[5];
; #pragma unroll
;       for (int tt = 0; tt < 4; ++tt) { aw[tt] = 0.f; aa[tt] = 0.f; }
; #pragma unroll
;       for (int tt = 0; tt < 5; ++tt) {
;         const int tok = tok0 + tt - 1;
;         const bool ok = (tt > 0) || (tok0 % T != 0);
;         const u16* pq = proj + (size_t)(ok ? tok : tok0) * INW + RW0;
;         pr_[tt] = ok ? bf2f(pq[c]) : 0.f; pk_[tt] = ok ? bf2f(pq[384 + c]) : 0.f; pv_[tt] = ok ? bf2f(pq[768 + c]) : 0.f;
;       }
; #pragma unroll 4
;       for (int j = 0; j < 32; ++j) {
;         const float wu = w_up[j * 384 + c], au = a_up[j * 384 + c];
; #pragma unroll
;         for (int tt = 0; tt < 4; ++tt) {
;           aw[tt] += codes[tt * 64 + j] * wu;
;           aa[tt] += codes[tt * 64 + 32 + j] * au;
;         }
;       }
.LBB0_587:
	v_mad_i64_i32 v[32:33], s[0:1], s25, v97, v[26:27]
	s_or_b32 s24, s25, 1
	s_or_b32 s23, s25, 2
	v_mad_i64_i32 v[34:35], s[0:1], s24, v97, v[26:27]
	v_mad_i64_i32 v[36:37], s[0:1], s23, v97, v[26:27]
	global_load_ushort v44, v[32:33], off offset:2304
	global_load_ushort v45, v[32:33], off offset:3072
	global_load_ushort v47, v[32:33], off offset:3840
	global_load_ushort v58, v[34:35], off offset:2304
	global_load_ushort v59, v[34:35], off offset:3072
	global_load_ushort v53, v[34:35], off offset:3840
	global_load_ushort v51, v[36:37], off offset:2304
	global_load_ushort v52, v[36:37], off offset:3072
	s_or_b32 s22, s25, 3
	v_mad_i64_i32 v[32:33], s[0:1], s22, v97, v[26:27]
	global_load_ushort v9, v[36:37], off offset:3840
	global_load_ushort v5, v[32:33], off offset:2304
	global_load_ushort v48, v[32:33], off offset:3072
	global_load_ushort v0, v[32:33], off offset:3840
	s_mov_b32 s0, 0
	s_movk_i32 s1, 0x100
	v_mov_b64_e32 v[36:37], v[30:31]
	v_mov_b64_e32 v[42:43], v[28:29]
	v_mov_b32_e32 v39, v38
	v_mov_b32_e32 v34, v38
	v_mov_b32_e32 v35, v38
	v_mov_b32_e32 v40, v38
	v_mov_b32_e32 v41, v38
	v_mov_b32_e32 v32, v38
	v_mov_b32_e32 v33, v38
	s_waitcnt vmcnt(0)
	v_mov_b32_e32 v49, 0x100
	ds_read_b128 v[54:57], v49
	ds_read_b128 v[62:65], v49 offset:128
	ds_read_b128 v[70:73], v49 offset:256
	ds_read_b128 v[74:77], v49 offset:384
	ds_read_b128 v[78:81], v49 offset:512
	ds_read_b128 v[82:85], v49 offset:640
	ds_read_b128 v[104:107], v49 offset:768
	ds_read_b128 v[108:111], v49 offset:896
	s_waitcnt lgkmcnt(7)
	v_mov_b32_e32 v122, v54
	s_waitcnt lgkmcnt(5)
	v_mov_b32_e32 v123, v70
	v_mov_b32_e32 v124, v62
	s_waitcnt lgkmcnt(4)
	v_mov_b32_e32 v125, v74
	s_waitcnt lgkmcnt(3)
	v_mov_b32_e32 v126, v78
	s_waitcnt lgkmcnt(1)
	v_mov_b32_e32 v127, v104
	v_mov_b32_e32 v128, v82
	s_waitcnt lgkmcnt(0)
	v_mov_b32_e32 v129, v108
	v_mov_b32_e32 v70, v55
	v_mov_b32_e32 v74, v63
	v_mov_b32_e32 v104, v79
	v_mov_b32_e32 v108, v83
	v_mov_b32_e32 v54, v56
	v_mov_b32_e32 v55, v72
	v_mov_b32_e32 v62, v64
	v_mov_b32_e32 v63, v76
	v_mov_b32_e32 v78, v80
	v_mov_b32_e32 v79, v106
	v_mov_b32_e32 v82, v84
	v_mov_b32_e32 v83, v110
	v_mov_b32_e32 v72, v57
	v_mov_b32_e32 v76, v65
	v_mov_b32_e32 v106, v81
	v_mov_b32_e32 v110, v85
	v_pk_fma_f32 v[38:39], v[164:165], v[122:123], v[38:39] op_sel_hi:[0,1,1]
	v_pk_fma_f32 v[40:41], v[164:165], v[124:125], v[40:41] op_sel:[1,0,0] op_sel_hi:[1,1,1]
	v_pk_fma_f32 v[34:35], v[164:165], v[126:127], v[34:35] op_sel_hi:[0,1,1]
	v_pk_fma_f32 v[32:33], v[164:165], v[128:129], v[32:33] op_sel:[1,0,0] op_sel_hi:[1,1,1]
	v_pk_fma_f32 v[38:39], v[166:167], v[70:71], v[38:39] op_sel_hi:[0,1,1]
	v_pk_fma_f32 v[40:41], v[166:167], v[74:75], v[40:41] op_sel:[1,0,0] op_sel_hi:[1,1,1]
	v_pk_fma_f32 v[34:35], v[166:167], v[104:105], v[34:35] op_sel_hi:[0,1,1]
	v_pk_fma_f32 v[32:33], v[166:167], v[108:109], v[32:33] op_sel:[1,0,0] op_sel_hi:[1,1,1]
	v_pk_fma_f32 v[38:39], v[168:169], v[54:55], v[38:39] op_sel_hi:[0,1,1]
	v_pk_fma_f32 v[40:41], v[168:169], v[62:63], v[40:41] op_sel:[1,0,0] op_sel_hi:[1,1,1]
	v_pk_fma_f32 v[34:35], v[168:169], v[78:79], v[34:35] op_sel_hi:[0,1,1]
	v_pk_fma_f32 v[32:33], v[168:169], v[82:83], v[32:33] op_sel:[1,0,0] op_sel_hi:[1,1,1]
	v_pk_fma_f32 v[38:39], v[170:171], v[72:73], v[38:39] op_sel_hi:[0,1,1]
	v_pk_fma_f32 v[40:41], v[170:171], v[76:77], v[40:41] op_sel:[1,0,0] op_sel_hi:[1,1,1]
	v_pk_fma_f32 v[34:35], v[170:171], v[106:107], v[34:35] op_sel_hi:[0,1,1]
	v_pk_fma_f32 v[32:33], v[170:171], v[110:111], v[32:33] op_sel:[1,0,0] op_sel_hi:[1,1,1]
	v_mov_b32_e32 v49, 0x110
	ds_read_b128 v[54:57], v49
	ds_read_b128 v[62:65], v49 offset:128
	ds_read_b128 v[70:73], v49 offset:256
	ds_read_b128 v[74:77], v49 offset:384
	ds_read_b128 v[78:81], v49 offset:512
	ds_read_b128 v[82:85], v49 offset:640
	ds_read_b128 v[104:107], v49 offset:768
	ds_read_b128 v[108:111], v49 offset:896
	s_waitcnt lgkmcnt(7)
	v_mov_b32_e32 v122, v54
	s_waitcnt lgkmcnt(5)
	v_mov_b32_e32 v123, v70
	v_mov_b32_e32 v124, v62
	s_waitcnt lgkmcnt(4)
	v_mov_b32_e32 v125, v74
	s_waitcnt lgkmcnt(3)
	v_mov_b32_e32 v126, v78
	s_waitcnt lgkmcnt(1)
	v_mov_b32_e32 v127, v104
	v_mov_b32_e32 v128, v82
	s_waitcnt lgkmcnt(0)
	v_mov_b32_e32 v129, v108
	v_mov_b32_e32 v70, v55
	v_mov_b32_e32 v74, v63
	v_mov_b32_e32 v104, v79
	v_mov_b32_e32 v108, v83
	v_mov_b32_e32 v54, v56
	v_mov_b32_e32 v55, v72
	v_mov_b32_e32 v62, v64
	v_mov_b32_e32 v63, v76
	v_mov_b32_e32 v78, v80
	v_mov_b32_e32 v79, v106
	v_mov_b32_e32 v82, v84
	v_mov_b32_e32 v83, v110
	v_mov_b32_e32 v72, v57
	v_mov_b32_e32 v76, v65
	v_mov_b32_e32 v106, v81
	v_mov_b32_e32 v110, v85
	v_pk_fma_f32 v[38:39], v[172:173], v[122:123], v[38:39] op_sel_hi:[0,1,1]
	v_pk_fma_f32 v[40:41], v[172:173], v[124:125], v[40:41] op_sel:[1,0,0] op_sel_hi:[1,1,1]
	v_pk_fma_f32 v[34:35], v[172:173], v[126:127], v[34:35] op_sel_hi:[0,1,1]
	v_pk_fma_f32 v[32:33], v[172:173], v[128:129], v[32:33] op_sel:[1,0,0] op_sel_hi:[1,1,1]
	v_pk_fma_f32 v[38:39], v[174:175], v[70:71], v[38:39] op_sel_hi:[0,1,1]
	v_pk_fma_f32 v[40:41], v[174:175], v[74:75], v[40:41] op_sel:[1,0,0] op_sel_hi:[1,1,1]
	v_pk_fma_f32 v[34:35], v[174:175], v[104:105], v[34:35] op_sel_hi:[0,1,1]
	v_pk_fma_f32 v[32:33], v[174:175], v[108:109], v[32:33] op_sel:[1,0,0] op_sel_hi:[1,1,1]
	v_pk_fma_f32 v[38:39], v[176:177], v[54:55], v[38:39] op_sel_hi:[0,1,1]
	v_pk_fma_f32 v[40:41], v[176:177], v[62:63], v[40:41] op_sel:[1,0,0] op_sel_hi:[1,1,1]
	v_pk_fma_f32 v[34:35], v[176:177], v[78:79], v[34:35] op_sel_hi:[0,1,1]
	v_pk_fma_f32 v[32:33], v[176:177], v[82:83], v[32:33] op_sel:[1,0,0] op_sel_hi:[1,1,1]
	v_pk_fma_f32 v[38:39], v[178:179], v[72:73], v[38:39] op_sel_hi:[0,1,1]
	v_pk_fma_f32 v[40:41], v[178:179], v[76:77], v[40:41] op_sel:[1,0,0] op_sel_hi:[1,1,1]
	v_pk_fma_f32 v[34:35], v[178:179], v[106:107], v[34:35] op_sel_hi:[0,1,1]
	v_pk_fma_f32 v[32:33], v[178:179], v[110:111], v[32:33] op_sel:[1,0,0] op_sel_hi:[1,1,1]
	v_mov_b32_e32 v49, 0x120
	ds_read_b128 v[54:57], v49
	ds_read_b128 v[62:65], v49 offset:128
	ds_read_b128 v[70:73], v49 offset:256
	ds_read_b128 v[74:77], v49 offset:384
	ds_read_b128 v[78:81], v49 offset:512
	ds_read_b128 v[82:85], v49 offset:640
	ds_read_b128 v[104:107], v49 offset:768
	ds_read_b128 v[108:111], v49 offset:896
	s_waitcnt lgkmcnt(7)
; __device__ void rwprep_items(const Params& p, int l, unsigned char* ldsraw, int it_begin, int it_end, int it_step) {
;     ...
;       for (int j = 0; j < 32; ++j) {
;         const float wu = w_up[j * 384 + c], au = a_up[j * 384 + c];
; #pragma unroll
;         for (int tt = 0; tt < 4; ++tt) {
;           aw[tt] += codes[tt * 64 + j] * wu;
;           aa[tt] += codes[tt * 64 + 32 + j] * au;
;         }
;       }
	v_mov_b32_e32 v122, v54
	s_waitcnt lgkmcnt(5)
	v_mov_b32_e32 v123, v70
	v_mov_b32_e32 v124, v62
	s_waitcnt lgkmcnt(4)
	v_mov_b32_e32 v125, v74
	s_waitcnt lgkmcnt(3)
	v_mov_b32_e32 v126, v78
	s_waitcnt lgkmcnt(1)
	v_mov_b32_e32 v127, v104
	v_mov_b32_e32 v128, v82
	s_waitcnt lgkmcnt(0)
	v_mov_b32_e32 v129, v108
	v_mov_b32_e32 v70, v55
	v_mov_b32_e32 v74, v63
	v_mov_b32_e32 v104, v79
	v_mov_b32_e32 v108, v83
	v_mov_b32_e32 v54, v56
	v_mov_b32_e32 v55, v72
	v_mov_b32_e32 v62, v64
	v_mov_b32_e32 v63, v76
	v_mov_b32_e32 v78, v80
	v_mov_b32_e32 v79, v106
	v_mov_b32_e32 v82, v84
	v_mov_b32_e32 v83, v110
	v_mov_b32_e32 v72, v57
	v_mov_b32_e32 v76, v65
	v_mov_b32_e32 v106, v81
	v_mov_b32_e32 v110, v85
	v_pk_fma_f32 v[38:39], v[180:181], v[122:123], v[38:39] op_sel_hi:[0,1,1]
	v_pk_fma_f32 v[40:41], v[180:181], v[124:125], v[40:41] op_sel:[1,0,0] op_sel_hi:[1,1,1]
	v_pk_fma_f32 v[34:35], v[180:181], v[126:127], v[34:35] op_sel_hi:[0,1,1]
	v_pk_fma_f32 v[32:33], v[180:181], v[128:129], v[32:33] op_sel:[1,0,0] op_sel_hi:[1,1,1]
	v_pk_fma_f32 v[38:39], v[182:183], v[70:71], v[38:39] op_sel_hi:[0,1,1]
	v_pk_fma_f32 v[40:41], v[182:183], v[74:75], v[40:41] op_sel:[1,0,0] op_sel_hi:[1,1,1]
	v_pk_fma_f32 v[34:35], v[182:183], v[104:105], v[34:35] op_sel_hi:[0,1,1]
	v_pk_fma_f32 v[32:33], v[182:183], v[108:109], v[32:33] op_sel:[1,0,0] op_sel_hi:[1,1,1]
	v_pk_fma_f32 v[38:39], v[184:185], v[54:55], v[38:39] op_sel_hi:[0,1,1]
	v_pk_fma_f32 v[40:41], v[184:185], v[62:63], v[40:41] op_sel:[1,0,0] op_sel_hi:[1,1,1]
	v_pk_fma_f32 v[34:35], v[184:185], v[78:79], v[34:35] op_sel_hi:[0,1,1]
	v_pk_fma_f32 v[32:33], v[184:185], v[82:83], v[32:33] op_sel:[1,0,0] op_sel_hi:[1,1,1]
	v_pk_fma_f32 v[38:39], v[186:187], v[72:73], v[38:39] op_sel_hi:[0,1,1]
	v_pk_fma_f32 v[40:41], v[186:187], v[76:77], v[40:41] op_sel:[1,0,0] op_sel_hi:[1,1,1]
	v_pk_fma_f32 v[34:35], v[186:187], v[106:107], v[34:35] op_sel_hi:[0,1,1]
	v_pk_fma_f32 v[32:33], v[186:187], v[110:111], v[32:33] op_sel:[1,0,0] op_sel_hi:[1,1,1]
	v_mov_b32_e32 v49, 0x130
	ds_read_b128 v[54:57], v49
	ds_read_b128 v[62:65], v49 offset:128
	ds_read_b128 v[70:73], v49 offset:256
	ds_read_b128 v[74:77], v49 offset:384
	ds_read_b128 v[78:81], v49 offset:512
	ds_read_b128 v[82:85], v49 offset:640
	ds_read_b128 v[104:107], v49 offset:768
	ds_read_b128 v[108:111], v49 offset:896
	s_waitcnt lgkmcnt(7)
	v_mov_b32_e32 v122, v54
	s_waitcnt lgkmcnt(5)
	v_mov_b32_e32 v123, v70
	v_mov_b32_e32 v124, v62
	s_waitcnt lgkmcnt(4)
	v_mov_b32_e32 v125, v74
	s_waitcnt lgkmcnt(3)
	v_mov_b32_e32 v126, v78
	s_waitcnt lgkmcnt(1)
	v_mov_b32_e32 v127, v104
	v_mov_b32_e32 v128, v82
	s_waitcnt lgkmcnt(0)
	v_mov_b32_e32 v129, v108
	v_mov_b32_e32 v70, v55
	v_mov_b32_e32 v74, v63
	v_mov_b32_e32 v104, v79
	v_mov_b32_e32 v108, v83
	v_mov_b32_e32 v54, v56
	v_mov_b32_e32 v55, v72
	v_mov_b32_e32 v62, v64
	v_mov_b32_e32 v63, v76
	v_mov_b32_e32 v78, v80
	v_mov_b32_e32 v79, v106
	v_mov_b32_e32 v82, v84
	v_mov_b32_e32 v83, v110
	v_mov_b32_e32 v72, v57
	v_mov_b32_e32 v76, v65
	v_mov_b32_e32 v106, v81
	v_mov_b32_e32 v110, v85
	v_pk_fma_f32 v[38:39], v[188:189], v[122:123], v[38:39] op_sel_hi:[0,1,1]
	v_pk_fma_f32 v[40:41], v[188:189], v[124:125], v[40:41] op_sel:[1,0,0] op_sel_hi:[1,1,1]
	v_pk_fma_f32 v[34:35], v[188:189], v[126:127], v[34:35] op_sel_hi:[0,1,1]
	v_pk_fma_f32 v[32:33], v[188:189], v[128:129], v[32:33] op_sel:[1,0,0] op_sel_hi:[1,1,1]
	v_pk_fma_f32 v[38:39], v[190:191], v[70:71], v[38:39] op_sel_hi:[0,1,1]
	v_pk_fma_f32 v[40:41], v[190:191], v[74:75], v[40:41] op_sel:[1,0,0] op_sel_hi:[1,1,1]
	v_pk_fma_f32 v[34:35], v[190:191], v[104:105], v[34:35] op_sel_hi:[0,1,1]
	v_pk_fma_f32 v[32:33], v[190:191], v[108:109], v[32:33] op_sel:[1,0,0] op_sel_hi:[1,1,1]
	v_pk_fma_f32 v[38:39], v[192:193], v[54:55], v[38:39] op_sel_hi:[0,1,1]
	v_pk_fma_f32 v[40:41], v[192:193], v[62:63], v[40:41] op_sel:[1,0,0] op_sel_hi:[1,1,1]
	v_pk_fma_f32 v[34:35], v[192:193], v[78:79], v[34:35] op_sel_hi:[0,1,1]
	v_pk_fma_f32 v[32:33], v[192:193], v[82:83], v[32:33] op_sel:[1,0,0] op_sel_hi:[1,1,1]
	v_pk_fma_f32 v[38:39], v[194:195], v[72:73], v[38:39] op_sel_hi:[0,1,1]
	v_pk_fma_f32 v[40:41], v[194:195], v[76:77], v[40:41] op_sel:[1,0,0] op_sel_hi:[1,1,1]
	v_pk_fma_f32 v[34:35], v[194:195], v[106:107], v[34:35] op_sel_hi:[0,1,1]
	v_pk_fma_f32 v[32:33], v[194:195], v[110:111], v[32:33] op_sel:[1,0,0] op_sel_hi:[1,1,1]
	v_mov_b32_e32 v49, 0x140
	ds_read_b128 v[54:57], v49
	ds_read_b128 v[62:65], v49 offset:128
	ds_read_b128 v[70:73], v49 offset:256
	ds_read_b128 v[74:77], v49 offset:384
	ds_read_b128 v[78:81], v49 offset:512
	ds_read_b128 v[82:85], v49 offset:640
	ds_read_b128 v[104:107], v49 offset:768
	ds_read_b128 v[108:111], v49 offset:896
	s_waitcnt lgkmcnt(7)
	v_mov_b32_e32 v122, v54
	s_waitcnt lgkmcnt(5)
	v_mov_b32_e32 v123, v70
	v_mov_b32_e32 v124, v62
	s_waitcnt lgkmcnt(4)
	v_mov_b32_e32 v125, v74
	s_waitcnt lgkmcnt(3)
	v_mov_b32_e32 v126, v78
	s_waitcnt lgkmcnt(1)
	v_mov_b32_e32 v127, v104
	v_mov_b32_e32 v128, v82
	s_waitcnt lgkmcnt(0)
; __device__ void rwprep_items(const Params& p, int l, unsigned char* ldsraw, int it_begin, int it_end, int it_step) {
;     ...
;       for (int j = 0; j < 32; ++j) {
;         const float wu = w_up[j * 384 + c], au = a_up[j * 384 + c];
; #pragma unroll
;         for (int tt = 0; tt < 4; ++tt) {
;           aw[tt] += codes[tt * 64 + j] * wu;
;           aa[tt] += codes[tt * 64 + 32 + j] * au;
;         }
;       }
	v_mov_b32_e32 v129, v108
	v_mov_b32_e32 v70, v55
	v_mov_b32_e32 v74, v63
	v_mov_b32_e32 v104, v79
	v_mov_b32_e32 v108, v83
	v_mov_b32_e32 v54, v56
	v_mov_b32_e32 v55, v72
	v_mov_b32_e32 v62, v64
	v_mov_b32_e32 v63, v76
	v_mov_b32_e32 v78, v80
	v_mov_b32_e32 v79, v106
	v_mov_b32_e32 v82, v84
	v_mov_b32_e32 v83, v110
	v_mov_b32_e32 v72, v57
	v_mov_b32_e32 v76, v65
	v_mov_b32_e32 v106, v81
	v_mov_b32_e32 v110, v85
	v_pk_fma_f32 v[38:39], v[196:197], v[122:123], v[38:39] op_sel_hi:[0,1,1]
	v_pk_fma_f32 v[40:41], v[196:197], v[124:125], v[40:41] op_sel:[1,0,0] op_sel_hi:[1,1,1]
	v_pk_fma_f32 v[34:35], v[196:197], v[126:127], v[34:35] op_sel_hi:[0,1,1]
	v_pk_fma_f32 v[32:33], v[196:197], v[128:129], v[32:33] op_sel:[1,0,0] op_sel_hi:[1,1,1]
	v_pk_fma_f32 v[38:39], v[198:199], v[70:71], v[38:39] op_sel_hi:[0,1,1]
	v_pk_fma_f32 v[40:41], v[198:199], v[74:75], v[40:41] op_sel:[1,0,0] op_sel_hi:[1,1,1]
	v_pk_fma_f32 v[34:35], v[198:199], v[104:105], v[34:35] op_sel_hi:[0,1,1]
	v_pk_fma_f32 v[32:33], v[198:199], v[108:109], v[32:33] op_sel:[1,0,0] op_sel_hi:[1,1,1]
	v_pk_fma_f32 v[38:39], v[200:201], v[54:55], v[38:39] op_sel_hi:[0,1,1]
	v_pk_fma_f32 v[40:41], v[200:201], v[62:63], v[40:41] op_sel:[1,0,0] op_sel_hi:[1,1,1]
	v_pk_fma_f32 v[34:35], v[200:201], v[78:79], v[34:35] op_sel_hi:[0,1,1]
	v_pk_fma_f32 v[32:33], v[200:201], v[82:83], v[32:33] op_sel:[1,0,0] op_sel_hi:[1,1,1]
	v_pk_fma_f32 v[38:39], v[202:203], v[72:73], v[38:39] op_sel_hi:[0,1,1]
	v_pk_fma_f32 v[40:41], v[202:203], v[76:77], v[40:41] op_sel:[1,0,0] op_sel_hi:[1,1,1]
	v_pk_fma_f32 v[34:35], v[202:203], v[106:107], v[34:35] op_sel_hi:[0,1,1]
	v_pk_fma_f32 v[32:33], v[202:203], v[110:111], v[32:33] op_sel:[1,0,0] op_sel_hi:[1,1,1]
	v_mov_b32_e32 v49, 0x150
	ds_read_b128 v[54:57], v49
	ds_read_b128 v[62:65], v49 offset:128
	ds_read_b128 v[70:73], v49 offset:256
	ds_read_b128 v[74:77], v49 offset:384
	ds_read_b128 v[78:81], v49 offset:512
	ds_read_b128 v[82:85], v49 offset:640
	ds_read_b128 v[104:107], v49 offset:768
	ds_read_b128 v[108:111], v49 offset:896
	s_waitcnt lgkmcnt(7)
	v_mov_b32_e32 v122, v54
	s_waitcnt lgkmcnt(5)
	v_mov_b32_e32 v123, v70
	v_mov_b32_e32 v124, v62
	s_waitcnt lgkmcnt(4)
	v_mov_b32_e32 v125, v74
	s_waitcnt lgkmcnt(3)
	v_mov_b32_e32 v126, v78
	s_waitcnt lgkmcnt(1)
	v_mov_b32_e32 v127, v104
	v_mov_b32_e32 v128, v82
	s_waitcnt lgkmcnt(0)
	v_mov_b32_e32 v129, v108
	v_mov_b32_e32 v70, v55
	v_mov_b32_e32 v74, v63
	v_mov_b32_e32 v104, v79
	v_mov_b32_e32 v108, v83
	v_mov_b32_e32 v54, v56
	v_mov_b32_e32 v55, v72
	v_mov_b32_e32 v62, v64
	v_mov_b32_e32 v63, v76
	v_mov_b32_e32 v78, v80
	v_mov_b32_e32 v79, v106
	v_mov_b32_e32 v82, v84
	v_mov_b32_e32 v83, v110
	v_mov_b32_e32 v72, v57
	v_mov_b32_e32 v76, v65
	v_mov_b32_e32 v106, v81
	v_mov_b32_e32 v110, v85
	v_pk_fma_f32 v[38:39], v[204:205], v[122:123], v[38:39] op_sel_hi:[0,1,1]
	v_pk_fma_f32 v[40:41], v[204:205], v[124:125], v[40:41] op_sel:[1,0,0] op_sel_hi:[1,1,1]
	v_pk_fma_f32 v[34:35], v[204:205], v[126:127], v[34:35] op_sel_hi:[0,1,1]
	v_pk_fma_f32 v[32:33], v[204:205], v[128:129], v[32:33] op_sel:[1,0,0] op_sel_hi:[1,1,1]
	v_pk_fma_f32 v[38:39], v[206:207], v[70:71], v[38:39] op_sel_hi:[0,1,1]
	v_pk_fma_f32 v[40:41], v[206:207], v[74:75], v[40:41] op_sel:[1,0,0] op_sel_hi:[1,1,1]
	v_pk_fma_f32 v[34:35], v[206:207], v[104:105], v[34:35] op_sel_hi:[0,1,1]
	v_pk_fma_f32 v[32:33], v[206:207], v[108:109], v[32:33] op_sel:[1,0,0] op_sel_hi:[1,1,1]
	v_pk_fma_f32 v[38:39], v[208:209], v[54:55], v[38:39] op_sel_hi:[0,1,1]
	v_pk_fma_f32 v[40:41], v[208:209], v[62:63], v[40:41] op_sel:[1,0,0] op_sel_hi:[1,1,1]
	v_pk_fma_f32 v[34:35], v[208:209], v[78:79], v[34:35] op_sel_hi:[0,1,1]
	v_pk_fma_f32 v[32:33], v[208:209], v[82:83], v[32:33] op_sel:[1,0,0] op_sel_hi:[1,1,1]
	v_pk_fma_f32 v[38:39], v[210:211], v[72:73], v[38:39] op_sel_hi:[0,1,1]
	v_pk_fma_f32 v[40:41], v[210:211], v[76:77], v[40:41] op_sel:[1,0,0] op_sel_hi:[1,1,1]
	v_pk_fma_f32 v[34:35], v[210:211], v[106:107], v[34:35] op_sel_hi:[0,1,1]
	v_pk_fma_f32 v[32:33], v[210:211], v[110:111], v[32:33] op_sel:[1,0,0] op_sel_hi:[1,1,1]
	v_mov_b32_e32 v49, 0x160
	ds_read_b128 v[54:57], v49
	ds_read_b128 v[62:65], v49 offset:128
	ds_read_b128 v[70:73], v49 offset:256
	ds_read_b128 v[74:77], v49 offset:384
	ds_read_b128 v[78:81], v49 offset:512
	ds_read_b128 v[82:85], v49 offset:640
	ds_read_b128 v[104:107], v49 offset:768
	ds_read_b128 v[108:111], v49 offset:896
	s_waitcnt lgkmcnt(7)
	v_mov_b32_e32 v122, v54
	s_waitcnt lgkmcnt(5)
	v_mov_b32_e32 v123, v70
	v_mov_b32_e32 v124, v62
	s_waitcnt lgkmcnt(4)
	v_mov_b32_e32 v125, v74
	s_waitcnt lgkmcnt(3)
	v_mov_b32_e32 v126, v78
	s_waitcnt lgkmcnt(1)
	v_mov_b32_e32 v127, v104
	v_mov_b32_e32 v128, v82
	s_waitcnt lgkmcnt(0)
; __device__ void rwprep_items(const Params& p, int l, unsigned char* ldsraw, int it_begin, int it_end, int it_step) {
;     ...
; #pragma unroll 4
;       for (int j = 0; j < 32; ++j) {
;         const float wu = w_up[j * 384 + c], au = a_up[j * 384 + c];
; #pragma unroll
;         for (int tt = 0; tt < 4; ++tt) {
;           aw[tt] += codes[tt * 64 + j] * wu;
;           aa[tt] += codes[tt * 64 + 32 + j] * au;
;         }
;       }
;       const float mur = mu[c], muk = mu[384 + c], muv = mu[768 + c];
;       const float w0c = w0[c], a0c = a0[c], kkc = k_k[c], kac = k_a[c], rkc = r_k[c];
	v_mov_b32_e32 v129, v108
	v_mov_b32_e32 v70, v55
	v_mov_b32_e32 v74, v63
	v_mov_b32_e32 v104, v79
	v_mov_b32_e32 v108, v83
	v_mov_b32_e32 v54, v56
	v_mov_b32_e32 v55, v72
	v_mov_b32_e32 v62, v64
	v_mov_b32_e32 v63, v76
	v_mov_b32_e32 v78, v80
	v_mov_b32_e32 v79, v106
	v_mov_b32_e32 v82, v84
	v_mov_b32_e32 v83, v110
	v_mov_b32_e32 v72, v57
	v_mov_b32_e32 v76, v65
	v_mov_b32_e32 v106, v81
	v_mov_b32_e32 v110, v85
	v_pk_fma_f32 v[38:39], v[212:213], v[122:123], v[38:39] op_sel_hi:[0,1,1]
	v_pk_fma_f32 v[40:41], v[212:213], v[124:125], v[40:41] op_sel:[1,0,0] op_sel_hi:[1,1,1]
	v_pk_fma_f32 v[34:35], v[212:213], v[126:127], v[34:35] op_sel_hi:[0,1,1]
	v_pk_fma_f32 v[32:33], v[212:213], v[128:129], v[32:33] op_sel:[1,0,0] op_sel_hi:[1,1,1]
	v_pk_fma_f32 v[38:39], v[214:215], v[70:71], v[38:39] op_sel_hi:[0,1,1]
	v_pk_fma_f32 v[40:41], v[214:215], v[74:75], v[40:41] op_sel:[1,0,0] op_sel_hi:[1,1,1]
	v_pk_fma_f32 v[34:35], v[214:215], v[104:105], v[34:35] op_sel_hi:[0,1,1]
	v_pk_fma_f32 v[32:33], v[214:215], v[108:109], v[32:33] op_sel:[1,0,0] op_sel_hi:[1,1,1]
	v_pk_fma_f32 v[38:39], v[216:217], v[54:55], v[38:39] op_sel_hi:[0,1,1]
	v_pk_fma_f32 v[40:41], v[216:217], v[62:63], v[40:41] op_sel:[1,0,0] op_sel_hi:[1,1,1]
	v_pk_fma_f32 v[34:35], v[216:217], v[78:79], v[34:35] op_sel_hi:[0,1,1]
	v_pk_fma_f32 v[32:33], v[216:217], v[82:83], v[32:33] op_sel:[1,0,0] op_sel_hi:[1,1,1]
	v_pk_fma_f32 v[38:39], v[218:219], v[72:73], v[38:39] op_sel_hi:[0,1,1]
	v_pk_fma_f32 v[40:41], v[218:219], v[76:77], v[40:41] op_sel:[1,0,0] op_sel_hi:[1,1,1]
	v_pk_fma_f32 v[34:35], v[218:219], v[106:107], v[34:35] op_sel_hi:[0,1,1]
	v_pk_fma_f32 v[32:33], v[218:219], v[110:111], v[32:33] op_sel:[1,0,0] op_sel_hi:[1,1,1]
	v_mov_b32_e32 v49, 0x170
	ds_read_b128 v[54:57], v49
	ds_read_b128 v[62:65], v49 offset:128
	ds_read_b128 v[70:73], v49 offset:256
	ds_read_b128 v[74:77], v49 offset:384
	ds_read_b128 v[78:81], v49 offset:512
	ds_read_b128 v[82:85], v49 offset:640
	ds_read_b128 v[104:107], v49 offset:768
	ds_read_b128 v[108:111], v49 offset:896
	s_waitcnt lgkmcnt(7)
	v_mov_b32_e32 v122, v54
	s_waitcnt lgkmcnt(5)
	v_mov_b32_e32 v123, v70
	v_mov_b32_e32 v124, v62
	s_waitcnt lgkmcnt(4)
	v_mov_b32_e32 v125, v74
	s_waitcnt lgkmcnt(3)
	v_mov_b32_e32 v126, v78
	s_waitcnt lgkmcnt(1)
	v_mov_b32_e32 v127, v104
	v_mov_b32_e32 v128, v82
	s_waitcnt lgkmcnt(0)
	v_mov_b32_e32 v129, v108
	v_mov_b32_e32 v70, v55
	v_mov_b32_e32 v74, v63
	v_mov_b32_e32 v104, v79
	v_mov_b32_e32 v108, v83
	v_mov_b32_e32 v54, v56
	v_mov_b32_e32 v55, v72
	v_mov_b32_e32 v62, v64
	v_mov_b32_e32 v63, v76
	v_mov_b32_e32 v78, v80
	v_mov_b32_e32 v79, v106
	v_mov_b32_e32 v82, v84
	v_mov_b32_e32 v83, v110
	v_mov_b32_e32 v72, v57
	v_mov_b32_e32 v76, v65
	v_mov_b32_e32 v106, v81
	v_mov_b32_e32 v110, v85
	v_pk_fma_f32 v[38:39], v[220:221], v[122:123], v[38:39] op_sel_hi:[0,1,1]
	v_pk_fma_f32 v[40:41], v[220:221], v[124:125], v[40:41] op_sel:[1,0,0] op_sel_hi:[1,1,1]
	v_pk_fma_f32 v[34:35], v[220:221], v[126:127], v[34:35] op_sel_hi:[0,1,1]
	v_pk_fma_f32 v[32:33], v[220:221], v[128:129], v[32:33] op_sel:[1,0,0] op_sel_hi:[1,1,1]
	v_pk_fma_f32 v[38:39], v[222:223], v[70:71], v[38:39] op_sel_hi:[0,1,1]
	v_pk_fma_f32 v[40:41], v[222:223], v[74:75], v[40:41] op_sel:[1,0,0] op_sel_hi:[1,1,1]
	v_pk_fma_f32 v[34:35], v[222:223], v[104:105], v[34:35] op_sel_hi:[0,1,1]
	v_pk_fma_f32 v[32:33], v[222:223], v[108:109], v[32:33] op_sel:[1,0,0] op_sel_hi:[1,1,1]
	v_pk_fma_f32 v[38:39], v[224:225], v[54:55], v[38:39] op_sel_hi:[0,1,1]
	v_pk_fma_f32 v[40:41], v[224:225], v[62:63], v[40:41] op_sel:[1,0,0] op_sel_hi:[1,1,1]
	v_pk_fma_f32 v[34:35], v[224:225], v[78:79], v[34:35] op_sel_hi:[0,1,1]
	v_pk_fma_f32 v[32:33], v[224:225], v[82:83], v[32:33] op_sel:[1,0,0] op_sel_hi:[1,1,1]
	v_pk_fma_f32 v[38:39], v[226:227], v[72:73], v[38:39] op_sel_hi:[0,1,1]
	v_pk_fma_f32 v[40:41], v[226:227], v[76:77], v[40:41] op_sel:[1,0,0] op_sel_hi:[1,1,1]
	v_pk_fma_f32 v[34:35], v[226:227], v[106:107], v[34:35] op_sel_hi:[0,1,1]
	v_pk_fma_f32 v[32:33], v[226:227], v[110:111], v[32:33] op_sel:[1,0,0] op_sel_hi:[1,1,1]
	global_load_dword v37, v[12:13], off
	global_load_dword v57, v[14:15], off
	global_load_dword v56, v[16:17], off
	global_load_dword v55, v[12:13], off offset:1536
	global_load_dword v36, v[18:19], off
	global_load_dword v54, v[20:21], off
	global_load_dword v50, v[22:23], off
	global_load_dword v49, v[12:13], off offset:3072
	v_lshlrev_b32_e32 v62, 16, v45
	v_lshlrev_b32_e32 v43, 16, v44
	v_mad_i64_i32 v[44:45], s[0:1], s25, v98, v[2:3]
	v_sub_f32_e32 v42, v61, v43
	v_sub_f32_e32 v63, v60, v62
	v_mad_u64_u32 v[60:61], s[0:1], v44, 12, s[84:85]
	s_mov_b32 s0, 0xbfb8aa3b
	v_mad_i32_i24 v61, v45, 12, v61
	s_waitcnt vmcnt(7)
; __device__ __forceinline__ u32 pack2(float lo, float hi) { return (u32)f2bf(lo) | ((u32)f2bf(hi) << 16); }
; __device__ __forceinline__ float wsum_u(float v) { return rdlane63(wsum_dpp63(v)); }
; __device__ void rwprep_items(const Params& p, int l, unsigned char* ldsraw, int it_begin, int it_end, int it_step) {
;     ...
; #pragma unroll
;       for (int tt = 0; tt < 4; ++tt) {
;         const int tok = tok0 + tt;
;         float r = pr_[tt + 1], k = pk_[tt + 1], v = pv_[tt + 1];
;         const float r1 = pr_[tt], k1 = pk_[tt], v1 = pv_[tt];
;         r += (r1 - r) * mur; k += (k1 - k) * muk; v += (v1 - v) * muv;
;         const float xw = w0c + aw[tt];
;         const float lw = -softplus_f(-xw) - 0.5f;
;         const float dec = __expf(-__expf(lw));
;         const float xa = a0c + aa[tt];
;         const float asig = 1.f / (1.f + __expf(-xa));
;         const float kkr = k * kkc;
;         const float ssum = wsum_u(kkr * kkr);
;         const float kk = kkr * rsqrtf(fmaxf(ssum, 1e-12f));
;         const float kmod = k * (1.f + (asig - 1.f) * kac);
;         const size_t o = ((size_t)tok * 384 + c) * 3;
;         rwp[o] = __float_as_uint(dec);
;         rwp[o + 1] = pack2(kk, kk * asig);
;         rwp[o + 2] = pack2(kmod, r);
;         const float bsum = wsum_u(r * kmod * rkc);
;         if ((tid & 63) == 0) bon[(size_t)tok * 6 + (tid >> 6)] = bsum;
	v_fma_f32 v42, v42, v37, v43
	s_waitcnt vmcnt(6)
	v_add_f32_e32 v38, v38, v57
	s_waitcnt vmcnt(5)
	v_add_f32_e32 v40, v40, v56
	v_mul_f32_e32 v40, 0xbfb8aa3b, v40
	s_waitcnt vmcnt(4)
	v_fma_f32 v65, v63, v55, v62
	v_max_f32_e64 v63, -v38, 0
	v_mul_f32_e64 v38, |v38|, s0
	v_exp_f32_e32 v40, v40
	s_waitcnt vmcnt(3)
	v_mul_f32_e32 v64, v65, v36
	v_exp_f32_e32 v38, v38
	v_mul_f32_e32 v67, v64, v64
	v_and_b32_sdwa v66, v42, v93 dst_sel:DWORD dst_unused:UNUSED_PAD src0_sel:WORD_1 src1_sel:DWORD
	v_add3_u32 v66, v42, v66, s96
	v_mov_b32_dpp v67, v67 quad_perm:[1,0,3,2] row_mask:0xf bank_mask:0xf bound_ctrl:1
	v_fmac_f32_e32 v67, v64, v64
	v_add_f32_e32 v40, 1.0, v40
	v_and_b32_e32 v70, 0xffff0000, v66
	v_add_f32_dpp v66, v67, v67 quad_perm:[2,3,0,1] row_mask:0xf bank_mask:0xf bound_ctrl:1
	v_add_f32_e32 v38, 1.0, v38
	v_div_scale_f32 v67, s[0:1], v40, v40, 1.0
	v_add_f32_dpp v66, v66, v66 row_half_mirror row_mask:0xf bank_mask:0xf bound_ctrl:1
	v_cmp_gt_f32_e64 s[0:1], s82, v38
	v_rcp_f32_e32 v74, v67
	v_add_f32_dpp v66, v66, v66 row_ror:8 row_mask:0xf bank_mask:0xf bound_ctrl:1
	v_cndmask_b32_e64 v72, 0, 32, s[0:1]
	v_ldexp_f32 v38, v38, v72
	v_add_f32_dpp v66, v66, v66 row_bcast:15 row_mask:0xf bank_mask:0xf bound_ctrl:1
	v_log_f32_e32 v38, v38
	v_cndmask_b32_e64 v73, 0, v95, s[0:1]
	v_add_f32_dpp v66, v66, v66 row_bcast:31 row_mask:0xf bank_mask:0xf bound_ctrl:1
	v_fma_f32 v72, -v67, v74, 1.0
	v_readlane_b32 s0, v66, 63
	v_div_scale_f32 v71, vcc, 1.0, v40, 1.0
	s_nop 0
	v_max_f32_e64 v66, s0, s0
	v_max_f32_e32 v66, 0x2b8cbccc, v66
	v_fmac_f32_e32 v74, v72, v74
	v_rsq_f32_e32 v66, v66
	v_mul_f32_e32 v72, 0x3f317217, v38
	v_mul_f32_e32 v75, v71, v74
	v_fma_f32 v72, v38, s20, -v72
	v_fma_f32 v76, -v67, v75, v71
	v_fmac_f32_e32 v72, 0x3377d1cf, v38
	v_fmac_f32_e32 v75, v76, v74
	v_fmac_f32_e32 v72, 0x3f317217, v38
	v_fma_f32 v67, -v67, v75, v71
	v_cmp_lt_f32_e64 s[0:1], |v38|, s21
	v_mul_f32_e32 v64, v64, v66
	v_div_fmas_f32 v66, v67, v74, v75
	v_cndmask_b32_e64 v38, v38, v72, s[0:1]
	v_sub_f32_e32 v38, v38, v73
	v_div_fixup_f32 v66, v66, v40, 1.0
	v_and_b32_sdwa v67, v64, v93 dst_sel:DWORD dst_unused:UNUSED_PAD src0_sel:WORD_1 src1_sel:DWORD
	v_add_f32_e32 v38, v63, v38
	v_add_f32_e32 v63, -1.0, v66
	v_add3_u32 v40, v64, v67, s96
	v_sub_f32_e32 v38, -0.5, v38
	s_waitcnt vmcnt(2)
	v_fma_f32 v67, v54, v63, 1.0
	v_mul_f32_e32 v38, 0x3fb8aa3b, v38
	v_pk_mul_f32 v[64:65], v[66:67], v[64:65]
	v_exp_f32_e32 v38, v38
	v_and_b32_sdwa v63, v65, v93 dst_sel:DWORD dst_unused:UNUSED_PAD src0_sel:WORD_1 src1_sel:DWORD
	v_mul_f32_e32 v42, v42, v65
	v_and_b32_sdwa v66, v64, v93 dst_sel:DWORD dst_unused:UNUSED_PAD src0_sel:WORD_1 src1_sel:DWORD
	v_add3_u32 v63, v65, v63, s96
	s_waitcnt vmcnt(1)
	v_mul_f32_e32 v65, v50, v42
	v_add3_u32 v64, v64, v66, s96
	v_or_b32_sdwa v66, v63, v70 dst_sel:DWORD dst_unused:UNUSED_PAD src0_sel:WORD_1 src1_sel:DWORD
	v_mov_b32_dpp v63, v65 quad_perm:[1,0,3,2] row_mask:0xf bank_mask:0xf bound_ctrl:1
	v_and_b32_e32 v64, 0xffff0000, v64
	v_fmac_f32_e32 v63, v50, v42
	v_or_b32_sdwa v65, v64, v40 dst_sel:DWORD dst_unused:UNUSED_PAD src0_sel:DWORD src1_sel:WORD_1
	v_mul_f32_e32 v38, 0xbfb8aa3b, v38
	v_add_f32_dpp v40, v63, v63 quad_perm:[2,3,0,1] row_mask:0xf bank_mask:0xf bound_ctrl:1
	v_exp_f32_e32 v64, v38
	global_store_dwordx3 v[60:61], v[64:66], off sc1
	v_add_f32_dpp v38, v40, v40 row_half_mirror row_mask:0xf bank_mask:0xf bound_ctrl:1
	s_nop 1
	v_add_f32_dpp v38, v38, v38 row_ror:8 row_mask:0xf bank_mask:0xf bound_ctrl:1
	s_nop 1
	v_add_f32_dpp v38, v38, v38 row_bcast:15 row_mask:0xf bank_mask:0xf bound_ctrl:1
	s_nop 1
	v_add_f32_dpp v38, v38, v38 row_bcast:31 row_mask:0xf bank_mask:0xf bound_ctrl:1
	s_nop 0
	v_readlane_b32 s26, v38, 63
	s_and_saveexec_b64 s[0:1], s[12:13]
	s_cbranch_execz .LBB0_591
	v_mad_i64_i32 v[60:61], s[28:29], s25, 24, v[24:25]
	v_mov_b32_e32 v38, s26
	global_store_dword v[60:61], v38, off sc1
